# GLA scan gate section (2a) rewritten: plain fmac chains instead of pk_fma+v_mov shuffles, lean softplus/exp for 1+exp(-|x|) in [1,2], rolling LDS prefetch
# speedup vs baseline: 1.0229x; 1.0229x over previous
.LBB0_3091:
	ds_read_b128 v[76:79], v203 offset:62464
	ds_read_b128 v[80:83], v203 offset:62480
	ds_read_b128 v[216:219], v203 offset:62496
	ds_read_b128 v[174:177], v203 offset:62512
	s_waitcnt lgkmcnt(3)
	v_fma_f32 v115, v76, v120, v134
	v_fma_f32 v117, v76, v154, v135
	v_fmac_f32_e32 v115, v77, v122
	v_fmac_f32_e32 v117, v77, v156
	v_fmac_f32_e32 v115, v78, v118
	v_fmac_f32_e32 v117, v78, v158
	v_fmac_f32_e32 v115, v79, v124
	v_fmac_f32_e32 v117, v79, v160
	ds_read_b128 v[76:79], v203 offset:62528
	s_waitcnt lgkmcnt(3)
	v_fmac_f32_e32 v115, v80, v121
	v_fmac_f32_e32 v117, v80, v155
	v_fmac_f32_e32 v115, v81, v123
	v_fmac_f32_e32 v117, v81, v157
	v_fmac_f32_e32 v115, v82, v119
	v_fmac_f32_e32 v117, v82, v159
	v_fmac_f32_e32 v115, v83, v125
	v_fmac_f32_e32 v117, v83, v161
	ds_read_b128 v[80:83], v203 offset:62544
	s_waitcnt lgkmcnt(3)
	v_fmac_f32_e32 v115, v216, v126
	v_fmac_f32_e32 v117, v216, v146
	v_fmac_f32_e32 v115, v217, v128
	v_fmac_f32_e32 v117, v217, v148
	v_fmac_f32_e32 v115, v218, v130
	v_fmac_f32_e32 v117, v218, v150
	v_fmac_f32_e32 v115, v219, v132
	v_fmac_f32_e32 v117, v219, v152
	ds_read_b128 v[216:219], v203 offset:62560
	s_waitcnt lgkmcnt(3)
	v_fmac_f32_e32 v115, v174, v127
	v_fmac_f32_e32 v117, v174, v147
	v_fmac_f32_e32 v115, v175, v129
	v_fmac_f32_e32 v117, v175, v149
	v_fmac_f32_e32 v115, v176, v131
	v_fmac_f32_e32 v117, v176, v151
	v_fmac_f32_e32 v115, v177, v133
	v_fmac_f32_e32 v117, v177, v153
	ds_read_b128 v[174:177], v203 offset:62576
	v_mul_f32_e64 v178, |v115|, s86
	v_mul_f32_e64 v179, |v117|, s86
	v_exp_f32_e32 v178, v178
	v_exp_f32_e32 v179, v179
	v_max_f32_e64 v115, -v115, 0
	v_add_f32_e32 v178, 1.0, v178
	v_add_f32_e32 v179, 1.0, v179
	v_max_f32_e64 v117, -v117, 0
	v_log_f32_e32 v178, v178
	v_log_f32_e32 v179, v179
	s_nop 0
	v_fmac_f32_e32 v115, 0x3f317217, v178
	v_fmac_f32_e32 v117, 0x3f317217, v179
	v_mul_f32_e32 v115, 0xbdb8aa3b, v115
	v_mul_f32_e32 v117, 0xbdb8aa3b, v117
	v_exp_f32_e32 v84, v115
	v_exp_f32_e32 v85, v117
	s_waitcnt lgkmcnt(3)
	v_fma_f32 v115, v76, v120, v134
	v_fma_f32 v117, v76, v154, v135
	v_fmac_f32_e32 v115, v77, v122
	v_fmac_f32_e32 v117, v77, v156
	v_mov_b32_e32 v220, v84
	v_mov_b32_e32 v221, v85
	v_fmac_f32_e32 v115, v78, v118
	v_fmac_f32_e32 v117, v78, v158
	v_fmac_f32_e32 v115, v79, v124
	v_fmac_f32_e32 v117, v79, v160
	ds_read_b128 v[76:79], v203 offset:62592
	s_waitcnt lgkmcnt(3)
	v_fmac_f32_e32 v115, v80, v121
	v_fmac_f32_e32 v117, v80, v155
	v_fmac_f32_e32 v115, v81, v123
	v_fmac_f32_e32 v117, v81, v157
	v_fmac_f32_e32 v115, v82, v119
	v_fmac_f32_e32 v117, v82, v159
	v_fmac_f32_e32 v115, v83, v125
	v_fmac_f32_e32 v117, v83, v161
	ds_read_b128 v[80:83], v203 offset:62608
	s_waitcnt lgkmcnt(3)
	v_fmac_f32_e32 v115, v216, v126
	v_fmac_f32_e32 v117, v216, v146
	v_fmac_f32_e32 v115, v217, v128
	v_fmac_f32_e32 v117, v217, v148
	v_fmac_f32_e32 v115, v218, v130
	v_fmac_f32_e32 v117, v218, v150
	v_fmac_f32_e32 v115, v219, v132
	v_fmac_f32_e32 v117, v219, v152
	ds_read_b128 v[216:219], v203 offset:62624
	s_waitcnt lgkmcnt(3)
	v_fmac_f32_e32 v115, v174, v127
	v_fmac_f32_e32 v117, v174, v147
	v_fmac_f32_e32 v115, v175, v129
	v_fmac_f32_e32 v117, v175, v149
	v_fmac_f32_e32 v115, v176, v131
	v_fmac_f32_e32 v117, v176, v151
	v_fmac_f32_e32 v115, v177, v133
	v_fmac_f32_e32 v117, v177, v153
	ds_read_b128 v[174:177], v203 offset:62640
	v_mul_f32_e64 v178, |v115|, s86
	v_mul_f32_e64 v179, |v117|, s86
	v_exp_f32_e32 v178, v178
	v_exp_f32_e32 v179, v179
	v_max_f32_e64 v115, -v115, 0
	v_add_f32_e32 v178, 1.0, v178
	v_add_f32_e32 v179, 1.0, v179
	v_max_f32_e64 v117, -v117, 0
	v_log_f32_e32 v178, v178
	v_log_f32_e32 v179, v179
	s_nop 0
	v_fmac_f32_e32 v115, 0x3f317217, v178
	v_fmac_f32_e32 v117, 0x3f317217, v179
	v_mul_f32_e32 v115, 0xbdb8aa3b, v115
	v_mul_f32_e32 v117, 0xbdb8aa3b, v117
	v_exp_f32_e32 v86, v115
	v_exp_f32_e32 v87, v117
	s_waitcnt lgkmcnt(3)
	v_fma_f32 v115, v76, v120, v134
	v_fma_f32 v117, v76, v154, v135
	v_fmac_f32_e32 v115, v77, v122
	v_fmac_f32_e32 v117, v77, v156
	v_pk_mul_f32 v[220:221], v[220:221], v[86:87]
	v_fmac_f32_e32 v115, v78, v118
	v_fmac_f32_e32 v117, v78, v158
	v_fmac_f32_e32 v115, v79, v124
	v_fmac_f32_e32 v117, v79, v160
	ds_read_b128 v[76:79], v203 offset:62656
	s_waitcnt lgkmcnt(3)
	v_fmac_f32_e32 v115, v80, v121
	v_fmac_f32_e32 v117, v80, v155
	v_fmac_f32_e32 v115, v81, v123
	v_fmac_f32_e32 v117, v81, v157
	v_fmac_f32_e32 v115, v82, v119
	v_fmac_f32_e32 v117, v82, v159
	v_fmac_f32_e32 v115, v83, v125
	v_fmac_f32_e32 v117, v83, v161
	ds_read_b128 v[80:83], v203 offset:62672
	s_waitcnt lgkmcnt(3)
	v_fmac_f32_e32 v115, v216, v126
	v_fmac_f32_e32 v117, v216, v146
	v_fmac_f32_e32 v115, v217, v128
	v_fmac_f32_e32 v117, v217, v148
	v_fmac_f32_e32 v115, v218, v130
	v_fmac_f32_e32 v117, v218, v150
	v_fmac_f32_e32 v115, v219, v132
	v_fmac_f32_e32 v117, v219, v152
	ds_read_b128 v[216:219], v203 offset:62688
	s_waitcnt lgkmcnt(3)
	v_fmac_f32_e32 v115, v174, v127
	v_fmac_f32_e32 v117, v174, v147
	v_fmac_f32_e32 v115, v175, v129
	v_fmac_f32_e32 v117, v175, v149
	v_fmac_f32_e32 v115, v176, v131
	v_fmac_f32_e32 v117, v176, v151
	v_fmac_f32_e32 v115, v177, v133
	v_fmac_f32_e32 v117, v177, v153
	ds_read_b128 v[174:177], v203 offset:62704
	v_mul_f32_e64 v178, |v115|, s86
	v_mul_f32_e64 v179, |v117|, s86
	v_exp_f32_e32 v178, v178
	v_exp_f32_e32 v179, v179
	v_max_f32_e64 v115, -v115, 0
	v_add_f32_e32 v178, 1.0, v178
	v_add_f32_e32 v179, 1.0, v179
	v_max_f32_e64 v117, -v117, 0
	v_log_f32_e32 v178, v178
	v_log_f32_e32 v179, v179
	s_nop 0
	v_fmac_f32_e32 v115, 0x3f317217, v178
	v_fmac_f32_e32 v117, 0x3f317217, v179
	v_mul_f32_e32 v115, 0xbdb8aa3b, v115
	v_mul_f32_e32 v117, 0xbdb8aa3b, v117
	v_exp_f32_e32 v88, v115
	v_exp_f32_e32 v89, v117
	s_waitcnt lgkmcnt(3)
	v_fma_f32 v115, v76, v120, v134
	v_fma_f32 v117, v76, v154, v135
	v_fmac_f32_e32 v115, v77, v122
	v_fmac_f32_e32 v117, v77, v156
	v_pk_mul_f32 v[220:221], v[220:221], v[88:89]
	v_fmac_f32_e32 v115, v78, v118
	v_fmac_f32_e32 v117, v78, v158
	v_fmac_f32_e32 v115, v79, v124
	v_fmac_f32_e32 v117, v79, v160
	ds_read_b128 v[76:79], v203 offset:62720
	s_waitcnt lgkmcnt(3)
	v_fmac_f32_e32 v115, v80, v121
	v_fmac_f32_e32 v117, v80, v155
	v_fmac_f32_e32 v115, v81, v123
	v_fmac_f32_e32 v117, v81, v157
	v_fmac_f32_e32 v115, v82, v119
	v_fmac_f32_e32 v117, v82, v159
	v_fmac_f32_e32 v115, v83, v125
	v_fmac_f32_e32 v117, v83, v161
	ds_read_b128 v[80:83], v203 offset:62736
	s_waitcnt lgkmcnt(3)
	v_fmac_f32_e32 v115, v216, v126
	v_fmac_f32_e32 v117, v216, v146
	v_fmac_f32_e32 v115, v217, v128
	v_fmac_f32_e32 v117, v217, v148
	v_fmac_f32_e32 v115, v218, v130
	v_fmac_f32_e32 v117, v218, v150
	v_fmac_f32_e32 v115, v219, v132
	v_fmac_f32_e32 v117, v219, v152
	ds_read_b128 v[216:219], v203 offset:62752
	s_waitcnt lgkmcnt(3)
	v_fmac_f32_e32 v115, v174, v127
	v_fmac_f32_e32 v117, v174, v147
	v_fmac_f32_e32 v115, v175, v129
	v_fmac_f32_e32 v117, v175, v149
	v_fmac_f32_e32 v115, v176, v131
	v_fmac_f32_e32 v117, v176, v151
	v_fmac_f32_e32 v115, v177, v133
	v_fmac_f32_e32 v117, v177, v153
	ds_read_b128 v[174:177], v203 offset:62768
	v_mul_f32_e64 v178, |v115|, s86
	v_mul_f32_e64 v179, |v117|, s86
	v_exp_f32_e32 v178, v178
	v_exp_f32_e32 v179, v179
	v_max_f32_e64 v115, -v115, 0
	v_add_f32_e32 v178, 1.0, v178
	v_add_f32_e32 v179, 1.0, v179
	v_max_f32_e64 v117, -v117, 0
	v_log_f32_e32 v178, v178
	v_log_f32_e32 v179, v179
	s_nop 0
	v_fmac_f32_e32 v115, 0x3f317217, v178
	v_fmac_f32_e32 v117, 0x3f317217, v179
	v_mul_f32_e32 v115, 0xbdb8aa3b, v115
	v_mul_f32_e32 v117, 0xbdb8aa3b, v117
	v_exp_f32_e32 v90, v115
	v_exp_f32_e32 v91, v117
	s_waitcnt lgkmcnt(3)
	v_fma_f32 v115, v76, v120, v134
	v_fma_f32 v117, v76, v154, v135
	v_fmac_f32_e32 v115, v77, v122
	v_fmac_f32_e32 v117, v77, v156
	v_pk_mul_f32 v[220:221], v[220:221], v[90:91]
	v_fmac_f32_e32 v115, v78, v118
	v_fmac_f32_e32 v117, v78, v158
	v_fmac_f32_e32 v115, v79, v124
	v_fmac_f32_e32 v117, v79, v160
	ds_read_b128 v[76:79], v203 offset:62784
	s_waitcnt lgkmcnt(3)
	v_fmac_f32_e32 v115, v80, v121
	v_fmac_f32_e32 v117, v80, v155
	v_fmac_f32_e32 v115, v81, v123
	v_fmac_f32_e32 v117, v81, v157
	v_fmac_f32_e32 v115, v82, v119
	v_fmac_f32_e32 v117, v82, v159
	v_fmac_f32_e32 v115, v83, v125
	v_fmac_f32_e32 v117, v83, v161
	ds_read_b128 v[80:83], v203 offset:62800
	s_waitcnt lgkmcnt(3)
	v_fmac_f32_e32 v115, v216, v126
	v_fmac_f32_e32 v117, v216, v146
	v_fmac_f32_e32 v115, v217, v128
	v_fmac_f32_e32 v117, v217, v148
	v_fmac_f32_e32 v115, v218, v130
	v_fmac_f32_e32 v117, v218, v150
	v_fmac_f32_e32 v115, v219, v132
	v_fmac_f32_e32 v117, v219, v152
	ds_read_b128 v[216:219], v203 offset:62816
	s_waitcnt lgkmcnt(3)
	v_fmac_f32_e32 v115, v174, v127
	v_fmac_f32_e32 v117, v174, v147
	v_fmac_f32_e32 v115, v175, v129
	v_fmac_f32_e32 v117, v175, v149
	v_fmac_f32_e32 v115, v176, v131
	v_fmac_f32_e32 v117, v176, v151
	v_fmac_f32_e32 v115, v177, v133
	v_fmac_f32_e32 v117, v177, v153
	ds_read_b128 v[174:177], v203 offset:62832
	v_mul_f32_e64 v178, |v115|, s86
	v_mul_f32_e64 v179, |v117|, s86
	v_exp_f32_e32 v178, v178
	v_exp_f32_e32 v179, v179
	v_max_f32_e64 v115, -v115, 0
	v_add_f32_e32 v178, 1.0, v178
	v_add_f32_e32 v179, 1.0, v179
	v_max_f32_e64 v117, -v117, 0
	v_log_f32_e32 v178, v178
	v_log_f32_e32 v179, v179
	s_nop 0
	v_fmac_f32_e32 v115, 0x3f317217, v178
	v_fmac_f32_e32 v117, 0x3f317217, v179
	v_mul_f32_e32 v115, 0xbdb8aa3b, v115
	v_mul_f32_e32 v117, 0xbdb8aa3b, v117
	v_exp_f32_e32 v92, v115
	v_exp_f32_e32 v93, v117
	s_waitcnt lgkmcnt(3)
	v_fma_f32 v115, v76, v120, v134
	v_fma_f32 v117, v76, v154, v135
	v_fmac_f32_e32 v115, v77, v122
	v_fmac_f32_e32 v117, v77, v156
	v_pk_mul_f32 v[220:221], v[220:221], v[92:93]
	v_fmac_f32_e32 v115, v78, v118
	v_fmac_f32_e32 v117, v78, v158
	v_fmac_f32_e32 v115, v79, v124
	v_fmac_f32_e32 v117, v79, v160
	ds_read_b128 v[76:79], v203 offset:62848
	s_waitcnt lgkmcnt(3)
	v_fmac_f32_e32 v115, v80, v121
	v_fmac_f32_e32 v117, v80, v155
	v_fmac_f32_e32 v115, v81, v123
	v_fmac_f32_e32 v117, v81, v157
	v_fmac_f32_e32 v115, v82, v119
	v_fmac_f32_e32 v117, v82, v159
	v_fmac_f32_e32 v115, v83, v125
	v_fmac_f32_e32 v117, v83, v161
	ds_read_b128 v[80:83], v203 offset:62864
	s_waitcnt lgkmcnt(3)
	v_fmac_f32_e32 v115, v216, v126
	v_fmac_f32_e32 v117, v216, v146
	v_fmac_f32_e32 v115, v217, v128
	v_fmac_f32_e32 v117, v217, v148
	v_fmac_f32_e32 v115, v218, v130
	v_fmac_f32_e32 v117, v218, v150
	v_fmac_f32_e32 v115, v219, v132
	v_fmac_f32_e32 v117, v219, v152
	ds_read_b128 v[216:219], v203 offset:62880
	s_waitcnt lgkmcnt(3)
	v_fmac_f32_e32 v115, v174, v127
	v_fmac_f32_e32 v117, v174, v147
	v_fmac_f32_e32 v115, v175, v129
	v_fmac_f32_e32 v117, v175, v149
	v_fmac_f32_e32 v115, v176, v131
	v_fmac_f32_e32 v117, v176, v151
	v_fmac_f32_e32 v115, v177, v133
	v_fmac_f32_e32 v117, v177, v153
	ds_read_b128 v[174:177], v203 offset:62896
	v_mul_f32_e64 v178, |v115|, s86
	v_mul_f32_e64 v179, |v117|, s86
	v_exp_f32_e32 v178, v178
	v_exp_f32_e32 v179, v179
	v_max_f32_e64 v115, -v115, 0
	v_add_f32_e32 v178, 1.0, v178
	v_add_f32_e32 v179, 1.0, v179
	v_max_f32_e64 v117, -v117, 0
	v_log_f32_e32 v178, v178
	v_log_f32_e32 v179, v179
	s_nop 0
	v_fmac_f32_e32 v115, 0x3f317217, v178
	v_fmac_f32_e32 v117, 0x3f317217, v179
	v_mul_f32_e32 v115, 0xbdb8aa3b, v115
	v_mul_f32_e32 v117, 0xbdb8aa3b, v117
	v_exp_f32_e32 v94, v115
	v_exp_f32_e32 v95, v117
	s_waitcnt lgkmcnt(3)
	v_fma_f32 v115, v76, v120, v134
	v_fma_f32 v117, v76, v154, v135
	v_fmac_f32_e32 v115, v77, v122
	v_fmac_f32_e32 v117, v77, v156
	v_pk_mul_f32 v[220:221], v[220:221], v[94:95]
	v_fmac_f32_e32 v115, v78, v118
	v_fmac_f32_e32 v117, v78, v158
	v_fmac_f32_e32 v115, v79, v124
	v_fmac_f32_e32 v117, v79, v160
	ds_read_b128 v[76:79], v203 offset:62912
	s_waitcnt lgkmcnt(3)
	v_fmac_f32_e32 v115, v80, v121
	v_fmac_f32_e32 v117, v80, v155
	v_fmac_f32_e32 v115, v81, v123
	v_fmac_f32_e32 v117, v81, v157
	v_fmac_f32_e32 v115, v82, v119
	v_fmac_f32_e32 v117, v82, v159
	v_fmac_f32_e32 v115, v83, v125
	v_fmac_f32_e32 v117, v83, v161
	ds_read_b128 v[80:83], v203 offset:62928
	s_waitcnt lgkmcnt(3)
	v_fmac_f32_e32 v115, v216, v126
	v_fmac_f32_e32 v117, v216, v146
	v_fmac_f32_e32 v115, v217, v128
	v_fmac_f32_e32 v117, v217, v148
	v_fmac_f32_e32 v115, v218, v130
	v_fmac_f32_e32 v117, v218, v150
	v_fmac_f32_e32 v115, v219, v132
	v_fmac_f32_e32 v117, v219, v152
	ds_read_b128 v[216:219], v203 offset:62944
	s_waitcnt lgkmcnt(3)
	v_fmac_f32_e32 v115, v174, v127
	v_fmac_f32_e32 v117, v174, v147
	v_fmac_f32_e32 v115, v175, v129
	v_fmac_f32_e32 v117, v175, v149
	v_fmac_f32_e32 v115, v176, v131
	v_fmac_f32_e32 v117, v176, v151
	v_fmac_f32_e32 v115, v177, v133
	v_fmac_f32_e32 v117, v177, v153
	ds_read_b128 v[174:177], v203 offset:62960
	v_mul_f32_e64 v178, |v115|, s86
	v_mul_f32_e64 v179, |v117|, s86
	v_exp_f32_e32 v178, v178
	v_exp_f32_e32 v179, v179
	v_max_f32_e64 v115, -v115, 0
	v_add_f32_e32 v178, 1.0, v178
	v_add_f32_e32 v179, 1.0, v179
	v_max_f32_e64 v117, -v117, 0
	v_log_f32_e32 v178, v178
	v_log_f32_e32 v179, v179
	s_nop 0
	v_fmac_f32_e32 v115, 0x3f317217, v178
	v_fmac_f32_e32 v117, 0x3f317217, v179
	v_mul_f32_e32 v115, 0xbdb8aa3b, v115
	v_mul_f32_e32 v117, 0xbdb8aa3b, v117
	v_exp_f32_e32 v96, v115
	v_exp_f32_e32 v97, v117
	s_waitcnt lgkmcnt(3)
	v_fma_f32 v115, v76, v120, v134
	v_fma_f32 v117, v76, v154, v135
	v_fmac_f32_e32 v115, v77, v122
	v_fmac_f32_e32 v117, v77, v156
	v_pk_mul_f32 v[220:221], v[220:221], v[96:97]
	v_fmac_f32_e32 v115, v78, v118
	v_fmac_f32_e32 v117, v78, v158
	v_fmac_f32_e32 v115, v79, v124
	v_fmac_f32_e32 v117, v79, v160
	ds_read_b128 v[76:79], v203 offset:62976
	s_waitcnt lgkmcnt(3)
	v_fmac_f32_e32 v115, v80, v121
	v_fmac_f32_e32 v117, v80, v155
	v_fmac_f32_e32 v115, v81, v123
	v_fmac_f32_e32 v117, v81, v157
	v_fmac_f32_e32 v115, v82, v119
	v_fmac_f32_e32 v117, v82, v159
	v_fmac_f32_e32 v115, v83, v125
	v_fmac_f32_e32 v117, v83, v161
	ds_read_b128 v[80:83], v203 offset:62992
	s_waitcnt lgkmcnt(3)
	v_fmac_f32_e32 v115, v216, v126
	v_fmac_f32_e32 v117, v216, v146
	v_fmac_f32_e32 v115, v217, v128
	v_fmac_f32_e32 v117, v217, v148
	v_fmac_f32_e32 v115, v218, v130
	v_fmac_f32_e32 v117, v218, v150
	v_fmac_f32_e32 v115, v219, v132
	v_fmac_f32_e32 v117, v219, v152
	ds_read_b128 v[216:219], v203 offset:63008
	s_waitcnt lgkmcnt(3)
	v_fmac_f32_e32 v115, v174, v127
	v_fmac_f32_e32 v117, v174, v147
	v_fmac_f32_e32 v115, v175, v129
	v_fmac_f32_e32 v117, v175, v149
	v_fmac_f32_e32 v115, v176, v131
	v_fmac_f32_e32 v117, v176, v151
	v_fmac_f32_e32 v115, v177, v133
	v_fmac_f32_e32 v117, v177, v153
	ds_read_b128 v[174:177], v203 offset:63024
	v_mul_f32_e64 v178, |v115|, s86
	v_mul_f32_e64 v179, |v117|, s86
	v_exp_f32_e32 v178, v178
	v_exp_f32_e32 v179, v179
	v_max_f32_e64 v115, -v115, 0
	v_add_f32_e32 v178, 1.0, v178
	v_add_f32_e32 v179, 1.0, v179
	v_max_f32_e64 v117, -v117, 0
	v_log_f32_e32 v178, v178
	v_log_f32_e32 v179, v179
	s_nop 0
	v_fmac_f32_e32 v115, 0x3f317217, v178
	v_fmac_f32_e32 v117, 0x3f317217, v179
	v_mul_f32_e32 v115, 0xbdb8aa3b, v115
	v_mul_f32_e32 v117, 0xbdb8aa3b, v117
	v_exp_f32_e32 v98, v115
	v_exp_f32_e32 v99, v117
	s_waitcnt lgkmcnt(3)
	v_fma_f32 v115, v76, v120, v134
	v_fma_f32 v117, v76, v154, v135
	v_fmac_f32_e32 v115, v77, v122
	v_fmac_f32_e32 v117, v77, v156
	v_pk_mul_f32 v[220:221], v[220:221], v[98:99]
	v_fmac_f32_e32 v115, v78, v118
	v_fmac_f32_e32 v117, v78, v158
	v_fmac_f32_e32 v115, v79, v124
	v_fmac_f32_e32 v117, v79, v160
	ds_read_b128 v[76:79], v203 offset:63040
	s_waitcnt lgkmcnt(3)
	v_fmac_f32_e32 v115, v80, v121
	v_fmac_f32_e32 v117, v80, v155
	v_fmac_f32_e32 v115, v81, v123
	v_fmac_f32_e32 v117, v81, v157
	v_fmac_f32_e32 v115, v82, v119
	v_fmac_f32_e32 v117, v82, v159
	v_fmac_f32_e32 v115, v83, v125
	v_fmac_f32_e32 v117, v83, v161
	ds_read_b128 v[80:83], v203 offset:63056
	s_waitcnt lgkmcnt(3)
	v_fmac_f32_e32 v115, v216, v126
	v_fmac_f32_e32 v117, v216, v146
	v_fmac_f32_e32 v115, v217, v128
	v_fmac_f32_e32 v117, v217, v148
	v_fmac_f32_e32 v115, v218, v130
	v_fmac_f32_e32 v117, v218, v150
	v_fmac_f32_e32 v115, v219, v132
	v_fmac_f32_e32 v117, v219, v152
	ds_read_b128 v[216:219], v203 offset:63072
	s_waitcnt lgkmcnt(3)
	v_fmac_f32_e32 v115, v174, v127
	v_fmac_f32_e32 v117, v174, v147
	v_fmac_f32_e32 v115, v175, v129
	v_fmac_f32_e32 v117, v175, v149
	v_fmac_f32_e32 v115, v176, v131
	v_fmac_f32_e32 v117, v176, v151
	v_fmac_f32_e32 v115, v177, v133
	v_fmac_f32_e32 v117, v177, v153
	ds_read_b128 v[174:177], v203 offset:63088
	v_mul_f32_e64 v178, |v115|, s86
	v_mul_f32_e64 v179, |v117|, s86
	v_exp_f32_e32 v178, v178
	v_exp_f32_e32 v179, v179
	v_max_f32_e64 v115, -v115, 0
	v_add_f32_e32 v178, 1.0, v178
	v_add_f32_e32 v179, 1.0, v179
	v_max_f32_e64 v117, -v117, 0
	v_log_f32_e32 v178, v178
	v_log_f32_e32 v179, v179
	s_nop 0
	v_fmac_f32_e32 v115, 0x3f317217, v178
	v_fmac_f32_e32 v117, 0x3f317217, v179
	v_mul_f32_e32 v115, 0xbdb8aa3b, v115
	v_mul_f32_e32 v117, 0xbdb8aa3b, v117
	v_exp_f32_e32 v162, v115
	v_exp_f32_e32 v163, v117
	s_waitcnt lgkmcnt(3)
	v_fma_f32 v115, v76, v120, v134
	v_fma_f32 v117, v76, v154, v135
	v_fmac_f32_e32 v115, v77, v122
	v_fmac_f32_e32 v117, v77, v156
	v_pk_mul_f32 v[220:221], v[220:221], v[162:163]
	v_fmac_f32_e32 v115, v78, v118
	v_fmac_f32_e32 v117, v78, v158
	v_fmac_f32_e32 v115, v79, v124
	v_fmac_f32_e32 v117, v79, v160
	ds_read_b128 v[76:79], v203 offset:63104
	s_waitcnt lgkmcnt(3)
	v_fmac_f32_e32 v115, v80, v121
	v_fmac_f32_e32 v117, v80, v155
	v_fmac_f32_e32 v115, v81, v123
	v_fmac_f32_e32 v117, v81, v157
	v_fmac_f32_e32 v115, v82, v119
	v_fmac_f32_e32 v117, v82, v159
	v_fmac_f32_e32 v115, v83, v125
	v_fmac_f32_e32 v117, v83, v161
	ds_read_b128 v[80:83], v203 offset:63120
	s_waitcnt lgkmcnt(3)
	v_fmac_f32_e32 v115, v216, v126
	v_fmac_f32_e32 v117, v216, v146
	v_fmac_f32_e32 v115, v217, v128
	v_fmac_f32_e32 v117, v217, v148
	v_fmac_f32_e32 v115, v218, v130
	v_fmac_f32_e32 v117, v218, v150
	v_fmac_f32_e32 v115, v219, v132
	v_fmac_f32_e32 v117, v219, v152
	ds_read_b128 v[216:219], v203 offset:63136
	s_waitcnt lgkmcnt(3)
	v_fmac_f32_e32 v115, v174, v127
	v_fmac_f32_e32 v117, v174, v147
	v_fmac_f32_e32 v115, v175, v129
	v_fmac_f32_e32 v117, v175, v149
	v_fmac_f32_e32 v115, v176, v131
	v_fmac_f32_e32 v117, v176, v151
	v_fmac_f32_e32 v115, v177, v133
	v_fmac_f32_e32 v117, v177, v153
	ds_read_b128 v[174:177], v203 offset:63152
	v_mul_f32_e64 v178, |v115|, s86
	v_mul_f32_e64 v179, |v117|, s86
	v_exp_f32_e32 v178, v178
	v_exp_f32_e32 v179, v179
	v_max_f32_e64 v115, -v115, 0
	v_add_f32_e32 v178, 1.0, v178
	v_add_f32_e32 v179, 1.0, v179
	v_max_f32_e64 v117, -v117, 0
	v_log_f32_e32 v178, v178
	v_log_f32_e32 v179, v179
	s_nop 0
	v_fmac_f32_e32 v115, 0x3f317217, v178
	v_fmac_f32_e32 v117, 0x3f317217, v179
	v_mul_f32_e32 v115, 0xbdb8aa3b, v115
	v_mul_f32_e32 v117, 0xbdb8aa3b, v117
	v_exp_f32_e32 v164, v115
	v_exp_f32_e32 v165, v117
	s_waitcnt lgkmcnt(3)
	v_fma_f32 v115, v76, v120, v134
	v_fma_f32 v117, v76, v154, v135
	v_fmac_f32_e32 v115, v77, v122
	v_fmac_f32_e32 v117, v77, v156
	v_pk_mul_f32 v[220:221], v[220:221], v[164:165]
	v_fmac_f32_e32 v115, v78, v118
	v_fmac_f32_e32 v117, v78, v158
	v_fmac_f32_e32 v115, v79, v124
	v_fmac_f32_e32 v117, v79, v160
	ds_read_b128 v[76:79], v203 offset:63168
	s_waitcnt lgkmcnt(3)
	v_fmac_f32_e32 v115, v80, v121
	v_fmac_f32_e32 v117, v80, v155
	v_fmac_f32_e32 v115, v81, v123
	v_fmac_f32_e32 v117, v81, v157
	v_fmac_f32_e32 v115, v82, v119
	v_fmac_f32_e32 v117, v82, v159
	v_fmac_f32_e32 v115, v83, v125
	v_fmac_f32_e32 v117, v83, v161
	ds_read_b128 v[80:83], v203 offset:63184
	s_waitcnt lgkmcnt(3)
	v_fmac_f32_e32 v115, v216, v126
	v_fmac_f32_e32 v117, v216, v146
	v_fmac_f32_e32 v115, v217, v128
	v_fmac_f32_e32 v117, v217, v148
	v_fmac_f32_e32 v115, v218, v130
	v_fmac_f32_e32 v117, v218, v150
	v_fmac_f32_e32 v115, v219, v132
	v_fmac_f32_e32 v117, v219, v152
	ds_read_b128 v[216:219], v203 offset:63200
	s_waitcnt lgkmcnt(3)
	v_fmac_f32_e32 v115, v174, v127
	v_fmac_f32_e32 v117, v174, v147
	v_fmac_f32_e32 v115, v175, v129
	v_fmac_f32_e32 v117, v175, v149
	v_fmac_f32_e32 v115, v176, v131
	v_fmac_f32_e32 v117, v176, v151
	v_fmac_f32_e32 v115, v177, v133
	v_fmac_f32_e32 v117, v177, v153
	ds_read_b128 v[174:177], v203 offset:63216
	v_mul_f32_e64 v178, |v115|, s86
	v_mul_f32_e64 v179, |v117|, s86
	v_exp_f32_e32 v178, v178
	v_exp_f32_e32 v179, v179
	v_max_f32_e64 v115, -v115, 0
	v_add_f32_e32 v178, 1.0, v178
	v_add_f32_e32 v179, 1.0, v179
	v_max_f32_e64 v117, -v117, 0
	v_log_f32_e32 v178, v178
	v_log_f32_e32 v179, v179
	s_nop 0
	v_fmac_f32_e32 v115, 0x3f317217, v178
	v_fmac_f32_e32 v117, 0x3f317217, v179
	v_mul_f32_e32 v115, 0xbdb8aa3b, v115
	v_mul_f32_e32 v117, 0xbdb8aa3b, v117
	v_exp_f32_e32 v166, v115
	v_exp_f32_e32 v167, v117
	s_waitcnt lgkmcnt(3)
	v_fma_f32 v115, v76, v120, v134
	v_fma_f32 v117, v76, v154, v135
	v_fmac_f32_e32 v115, v77, v122
	v_fmac_f32_e32 v117, v77, v156
	v_pk_mul_f32 v[220:221], v[220:221], v[166:167]
	v_fmac_f32_e32 v115, v78, v118
	v_fmac_f32_e32 v117, v78, v158
	v_fmac_f32_e32 v115, v79, v124
	v_fmac_f32_e32 v117, v79, v160
	ds_read_b128 v[76:79], v203 offset:63232
	s_waitcnt lgkmcnt(3)
	v_fmac_f32_e32 v115, v80, v121
	v_fmac_f32_e32 v117, v80, v155
	v_fmac_f32_e32 v115, v81, v123
	v_fmac_f32_e32 v117, v81, v157
	v_fmac_f32_e32 v115, v82, v119
	v_fmac_f32_e32 v117, v82, v159
	v_fmac_f32_e32 v115, v83, v125
	v_fmac_f32_e32 v117, v83, v161
	ds_read_b128 v[80:83], v203 offset:63248
	s_waitcnt lgkmcnt(3)
	v_fmac_f32_e32 v115, v216, v126
	v_fmac_f32_e32 v117, v216, v146
	v_fmac_f32_e32 v115, v217, v128
	v_fmac_f32_e32 v117, v217, v148
	v_fmac_f32_e32 v115, v218, v130
	v_fmac_f32_e32 v117, v218, v150
	v_fmac_f32_e32 v115, v219, v132
	v_fmac_f32_e32 v117, v219, v152
	ds_read_b128 v[216:219], v203 offset:63264
	s_waitcnt lgkmcnt(3)
	v_fmac_f32_e32 v115, v174, v127
	v_fmac_f32_e32 v117, v174, v147
	v_fmac_f32_e32 v115, v175, v129
	v_fmac_f32_e32 v117, v175, v149
	v_fmac_f32_e32 v115, v176, v131
	v_fmac_f32_e32 v117, v176, v151
	v_fmac_f32_e32 v115, v177, v133
	v_fmac_f32_e32 v117, v177, v153
	ds_read_b128 v[174:177], v203 offset:63280
	v_mul_f32_e64 v178, |v115|, s86
	v_mul_f32_e64 v179, |v117|, s86
	v_exp_f32_e32 v178, v178
	v_exp_f32_e32 v179, v179
	v_max_f32_e64 v115, -v115, 0
	v_add_f32_e32 v178, 1.0, v178
	v_add_f32_e32 v179, 1.0, v179
	v_max_f32_e64 v117, -v117, 0
	v_log_f32_e32 v178, v178
	v_log_f32_e32 v179, v179
	s_nop 0
	v_fmac_f32_e32 v115, 0x3f317217, v178
	v_fmac_f32_e32 v117, 0x3f317217, v179
	v_mul_f32_e32 v115, 0xbdb8aa3b, v115
	v_mul_f32_e32 v117, 0xbdb8aa3b, v117
	v_exp_f32_e32 v168, v115
	v_exp_f32_e32 v169, v117
	s_waitcnt lgkmcnt(3)
	v_fma_f32 v115, v76, v120, v134
	v_fma_f32 v117, v76, v154, v135
	v_fmac_f32_e32 v115, v77, v122
	v_fmac_f32_e32 v117, v77, v156
	v_pk_mul_f32 v[220:221], v[220:221], v[168:169]
	v_fmac_f32_e32 v115, v78, v118
	v_fmac_f32_e32 v117, v78, v158
	v_fmac_f32_e32 v115, v79, v124
	v_fmac_f32_e32 v117, v79, v160
	ds_read_b128 v[76:79], v203 offset:63296
	s_waitcnt lgkmcnt(3)
	v_fmac_f32_e32 v115, v80, v121
	v_fmac_f32_e32 v117, v80, v155
	v_fmac_f32_e32 v115, v81, v123
	v_fmac_f32_e32 v117, v81, v157
	v_fmac_f32_e32 v115, v82, v119
	v_fmac_f32_e32 v117, v82, v159
	v_fmac_f32_e32 v115, v83, v125
	v_fmac_f32_e32 v117, v83, v161
	ds_read_b128 v[80:83], v203 offset:63312
	s_waitcnt lgkmcnt(3)
	v_fmac_f32_e32 v115, v216, v126
	v_fmac_f32_e32 v117, v216, v146
	v_fmac_f32_e32 v115, v217, v128
	v_fmac_f32_e32 v117, v217, v148
	v_fmac_f32_e32 v115, v218, v130
	v_fmac_f32_e32 v117, v218, v150
	v_fmac_f32_e32 v115, v219, v132
	v_fmac_f32_e32 v117, v219, v152
	ds_read_b128 v[216:219], v203 offset:63328
	s_waitcnt lgkmcnt(3)
	v_fmac_f32_e32 v115, v174, v127
	v_fmac_f32_e32 v117, v174, v147
	v_fmac_f32_e32 v115, v175, v129
	v_fmac_f32_e32 v117, v175, v149
	v_fmac_f32_e32 v115, v176, v131
	v_fmac_f32_e32 v117, v176, v151
	v_fmac_f32_e32 v115, v177, v133
	v_fmac_f32_e32 v117, v177, v153
	ds_read_b128 v[174:177], v203 offset:63344
	v_mul_f32_e64 v178, |v115|, s86
	v_mul_f32_e64 v179, |v117|, s86
	v_exp_f32_e32 v178, v178
	v_exp_f32_e32 v179, v179
	v_max_f32_e64 v115, -v115, 0
	v_add_f32_e32 v178, 1.0, v178
	v_add_f32_e32 v179, 1.0, v179
	v_max_f32_e64 v117, -v117, 0
	v_log_f32_e32 v178, v178
	v_log_f32_e32 v179, v179
	s_nop 0
	v_fmac_f32_e32 v115, 0x3f317217, v178
	v_fmac_f32_e32 v117, 0x3f317217, v179
	v_mul_f32_e32 v115, 0xbdb8aa3b, v115
	v_mul_f32_e32 v117, 0xbdb8aa3b, v117
	v_exp_f32_e32 v170, v115
	v_exp_f32_e32 v171, v117
	s_waitcnt lgkmcnt(3)
	v_fma_f32 v115, v76, v120, v134
	v_fma_f32 v117, v76, v154, v135
	v_fmac_f32_e32 v115, v77, v122
	v_fmac_f32_e32 v117, v77, v156
	v_pk_mul_f32 v[220:221], v[220:221], v[170:171]
	v_fmac_f32_e32 v115, v78, v118
	v_fmac_f32_e32 v117, v78, v158
	v_fmac_f32_e32 v115, v79, v124
	v_fmac_f32_e32 v117, v79, v160
	ds_read_b128 v[76:79], v203 offset:63360
	s_waitcnt lgkmcnt(3)
	v_fmac_f32_e32 v115, v80, v121
	v_fmac_f32_e32 v117, v80, v155
	v_fmac_f32_e32 v115, v81, v123
	v_fmac_f32_e32 v117, v81, v157
	v_fmac_f32_e32 v115, v82, v119
	v_fmac_f32_e32 v117, v82, v159
	v_fmac_f32_e32 v115, v83, v125
	v_fmac_f32_e32 v117, v83, v161
	ds_read_b128 v[80:83], v203 offset:63376
	s_waitcnt lgkmcnt(3)
	v_fmac_f32_e32 v115, v216, v126
	v_fmac_f32_e32 v117, v216, v146
	v_fmac_f32_e32 v115, v217, v128
	v_fmac_f32_e32 v117, v217, v148
	v_fmac_f32_e32 v115, v218, v130
	v_fmac_f32_e32 v117, v218, v150
	v_fmac_f32_e32 v115, v219, v132
	v_fmac_f32_e32 v117, v219, v152
	ds_read_b128 v[216:219], v203 offset:63392
	s_waitcnt lgkmcnt(3)
	v_fmac_f32_e32 v115, v174, v127
	v_fmac_f32_e32 v117, v174, v147
	v_fmac_f32_e32 v115, v175, v129
	v_fmac_f32_e32 v117, v175, v149
	v_fmac_f32_e32 v115, v176, v131
	v_fmac_f32_e32 v117, v176, v151
	v_fmac_f32_e32 v115, v177, v133
	v_fmac_f32_e32 v117, v177, v153
	ds_read_b128 v[174:177], v203 offset:63408
	v_mul_f32_e64 v178, |v115|, s86
	v_mul_f32_e64 v179, |v117|, s86
	v_exp_f32_e32 v178, v178
	v_exp_f32_e32 v179, v179
	v_max_f32_e64 v115, -v115, 0
	v_add_f32_e32 v178, 1.0, v178
	v_add_f32_e32 v179, 1.0, v179
	v_max_f32_e64 v117, -v117, 0
	v_log_f32_e32 v178, v178
	v_log_f32_e32 v179, v179
	s_nop 0
	v_fmac_f32_e32 v115, 0x3f317217, v178
	v_fmac_f32_e32 v117, 0x3f317217, v179
	v_mul_f32_e32 v115, 0xbdb8aa3b, v115
	v_mul_f32_e32 v117, 0xbdb8aa3b, v117
	v_exp_f32_e32 v172, v115
	v_exp_f32_e32 v173, v117
	s_waitcnt lgkmcnt(3)
	v_fma_f32 v115, v76, v120, v134
	v_fma_f32 v117, v76, v154, v135
	v_fmac_f32_e32 v115, v77, v122
	v_fmac_f32_e32 v117, v77, v156
	v_pk_mul_f32 v[220:221], v[220:221], v[172:173]
	v_fmac_f32_e32 v115, v78, v118
	v_fmac_f32_e32 v117, v78, v158
	v_fmac_f32_e32 v115, v79, v124
	v_fmac_f32_e32 v117, v79, v160
	ds_read_b128 v[76:79], v203 offset:63424
	s_waitcnt lgkmcnt(3)
	v_fmac_f32_e32 v115, v80, v121
	v_fmac_f32_e32 v117, v80, v155
	v_fmac_f32_e32 v115, v81, v123
	v_fmac_f32_e32 v117, v81, v157
	v_fmac_f32_e32 v115, v82, v119
	v_fmac_f32_e32 v117, v82, v159
	v_fmac_f32_e32 v115, v83, v125
	v_fmac_f32_e32 v117, v83, v161
	ds_read_b128 v[80:83], v203 offset:63440
	s_waitcnt lgkmcnt(3)
	v_fmac_f32_e32 v115, v216, v126
	v_fmac_f32_e32 v117, v216, v146
	v_fmac_f32_e32 v115, v217, v128
	v_fmac_f32_e32 v117, v217, v148
	v_fmac_f32_e32 v115, v218, v130
	v_fmac_f32_e32 v117, v218, v150
	v_fmac_f32_e32 v115, v219, v132
	v_fmac_f32_e32 v117, v219, v152
	ds_read_b128 v[216:219], v203 offset:63456
	s_waitcnt lgkmcnt(3)
	v_fmac_f32_e32 v115, v174, v127
	v_fmac_f32_e32 v117, v174, v147
	v_fmac_f32_e32 v115, v175, v129
	v_fmac_f32_e32 v117, v175, v149
	v_fmac_f32_e32 v115, v176, v131
	v_fmac_f32_e32 v117, v176, v151
	v_fmac_f32_e32 v115, v177, v133
	v_fmac_f32_e32 v117, v177, v153
	v_mul_f32_e64 v178, |v115|, s86
	v_mul_f32_e64 v179, |v117|, s86
	v_exp_f32_e32 v178, v178
	v_exp_f32_e32 v179, v179
	v_max_f32_e64 v115, -v115, 0
	v_add_f32_e32 v178, 1.0, v178
	v_add_f32_e32 v179, 1.0, v179
	v_max_f32_e64 v117, -v117, 0
	v_log_f32_e32 v178, v178
	v_log_f32_e32 v179, v179
	s_nop 0
	v_fmac_f32_e32 v115, 0x3f317217, v178
	v_fmac_f32_e32 v117, 0x3f317217, v179
	v_mul_f32_e32 v115, 0xbdb8aa3b, v115
	v_mul_f32_e32 v117, 0xbdb8aa3b, v117
	v_exp_f32_e32 v174, v115
	v_exp_f32_e32 v175, v117
	s_waitcnt lgkmcnt(2)
	v_fma_f32 v115, v76, v120, v134
	v_fma_f32 v117, v76, v154, v135
	v_fmac_f32_e32 v115, v77, v122
	v_fmac_f32_e32 v117, v77, v156
	v_pk_mul_f32 v[220:221], v[220:221], v[174:175]
	v_fmac_f32_e32 v115, v78, v118
	v_fmac_f32_e32 v117, v78, v158
	v_fmac_f32_e32 v115, v79, v124
	v_fmac_f32_e32 v117, v79, v160
	ds_read_b128 v[76:79], v203 offset:63472
	s_waitcnt lgkmcnt(2)
	v_fmac_f32_e32 v115, v80, v121
	v_fmac_f32_e32 v117, v80, v155
	v_fmac_f32_e32 v115, v81, v123
	v_fmac_f32_e32 v117, v81, v157
	v_fmac_f32_e32 v115, v82, v119
	v_fmac_f32_e32 v117, v82, v159
	v_fmac_f32_e32 v115, v83, v125
	v_fmac_f32_e32 v117, v83, v161
	s_waitcnt lgkmcnt(1)
	v_fmac_f32_e32 v115, v216, v126
	v_fmac_f32_e32 v117, v216, v146
	v_fmac_f32_e32 v115, v217, v128
	v_fmac_f32_e32 v117, v217, v148
	v_fmac_f32_e32 v115, v218, v130
	v_fmac_f32_e32 v117, v218, v150
	v_fmac_f32_e32 v115, v219, v132
	v_fmac_f32_e32 v117, v219, v152
	s_waitcnt lgkmcnt(0)
	v_fmac_f32_e32 v115, v76, v127
	v_fmac_f32_e32 v117, v76, v147
	v_fmac_f32_e32 v115, v77, v129
	v_fmac_f32_e32 v117, v77, v149
	v_fmac_f32_e32 v115, v78, v131
	v_fmac_f32_e32 v117, v78, v151
	v_fmac_f32_e32 v115, v79, v133
	v_fmac_f32_e32 v117, v79, v153
	v_mul_f32_e64 v178, |v115|, s86
	v_mul_f32_e64 v179, |v117|, s86
	v_exp_f32_e32 v178, v178
	v_exp_f32_e32 v179, v179
	v_max_f32_e64 v115, -v115, 0
	v_add_f32_e32 v178, 1.0, v178
	v_add_f32_e32 v179, 1.0, v179
	v_max_f32_e64 v117, -v117, 0
	v_log_f32_e32 v178, v178
	v_log_f32_e32 v179, v179
	s_nop 0
	v_fmac_f32_e32 v115, 0x3f317217, v178
	v_fmac_f32_e32 v117, 0x3f317217, v179
	v_mul_f32_e32 v115, 0xbdb8aa3b, v115
	v_mul_f32_e32 v117, 0xbdb8aa3b, v117
	v_exp_f32_e32 v176, v115
	v_exp_f32_e32 v177, v117
	s_nop 1
	v_pk_mul_f32 v[220:221], v[220:221], v[176:177]
	s_nop 0
	ds_write_b64 v192, v[220:221]
	s_waitcnt lgkmcnt(0)
	s_barrier
	ds_read2st64_b64 v[80:83], v191 offset1:1
	ds_read2st64_b64 v[76:79], v191 offset0:2 offset1:3
	s_waitcnt lgkmcnt(1)
	v_pk_mul_f32 v[178:179], v[80:81], v[82:83]
	s_waitcnt lgkmcnt(0)
	v_pk_mul_f32 v[178:179], v[178:179], v[76:77]
	s_nop 0
	v_pk_mul_f32 v[178:179], v[178:179], v[78:79]
	s_and_saveexec_b64 s[48:49], s[4:5]
	ds_write_b64 v197, v[178:179]
	s_or_b64 exec, exec, s[48:49]
	v_cndmask_b32_e64 v81, v81, 1.0, s[4:5]
	v_cndmask_b32_e64 v80, v80, 1.0, s[4:5]
	v_mul_f32_e32 v82, v80, v82
	v_mul_f32_e32 v83, v81, v83
	v_cndmask_b32_e64 v81, v81, v83, s[6:7]
	v_cndmask_b32_e64 v80, v80, v82, s[6:7]
	v_pk_mul_f32 v[76:77], v[80:81], v[76:77]
	v_add_u32_e32 v115, 0x4400, v200
	v_cndmask_b32_e64 v77, v81, v77, s[8:9]
	v_cndmask_b32_e64 v76, v80, v76, s[8:9]
	v_pk_mul_f32 v[78:79], v[76:77], v[78:79]
	ds_read2_b32 v[82:83], v115 offset1:68
	v_cndmask_b32_e64 v77, v77, v79, s[10:11]
	v_cndmask_b32_e64 v76, v76, v78, s[10:11]
	ds_read2_b32 v[78:79], v200 offset1:68
	v_pk_mul_f32 v[76:77], v[84:85], v[76:77]
	s_cmp_lt_u32 s93, 4
	v_rcp_f32_e32 v80, v76
	v_rcp_f32_e32 v81, v77
	s_waitcnt lgkmcnt(0)
	v_lshlrev_b32_e32 v84, 16, v78
	v_and_b32_e32 v78, 0xffff0000, v78
	v_mul_f32_e32 v84, v76, v84
	v_mul_f32_e32 v78, v77, v78
	v_cvt_pk_bf16_f32 v117, v84, v78
	v_lshlrev_b32_e32 v78, 16, v82
	v_and_b32_e32 v82, 0xffff0000, v82
	v_mov_b32_e32 v84, v78
	v_mov_b32_e32 v85, v82
	v_pk_mul_f32 v[84:85], v[80:81], v[84:85]
	v_pk_mul_f32 v[76:77], v[86:87], v[76:77]
	v_lshlrev_b32_e32 v218, 16, v79
	v_and_b32_e32 v219, 0xffff0000, v79
	v_cvt_pk_bf16_f32 v220, v84, v85
	v_rcp_f32_e32 v85, v76
	v_mul_f32_e32 v84, v76, v218
	v_mul_f32_e32 v86, v77, v219
	v_rcp_f32_e32 v87, v77
	v_cvt_pk_bf16_f32 v84, v84, v86
	ds_write2_b32 v200, v117, v84 offset1:68
	v_mov_b32_e32 v84, v80
	v_lshlrev_b32_e32 v79, 16, v83
	v_and_b32_e32 v83, 0xffff0000, v83
	v_pk_mul_f32 v[218:219], v[178:179], v[84:85] op_sel_hi:[0,1]
	v_mov_b32_e32 v216, v79
	v_mov_b32_e32 v217, v83
	v_pk_mul_f32 v[78:79], v[218:219], v[78:79]
	v_mov_b32_e32 v86, v85
	v_cvt_pk_bf16_f32 v84, v78, v79
	v_pk_mul_f32 v[78:79], v[86:87], v[216:217]
	v_mov_b32_e32 v86, v81
	v_pk_mul_f32 v[80:81], v[178:179], v[86:87] op_sel:[1,0]
	v_cvt_pk_bf16_f32 v78, v78, v79
	v_pk_mul_f32 v[80:81], v[80:81], v[82:83]
	v_pk_mul_f32 v[76:77], v[88:89], v[76:77]
	v_cvt_pk_bf16_f32 v80, v80, v81
	ds_write2_b32 v115, v220, v78 offset1:68
	ds_write_b32 v193, v84 offset:34816
	ds_write_b32 v193, v80 offset:34960
	ds_read2_b32 v[78:79], v200 offset0:136 offset1:204
	v_rcp_f32_e32 v80, v76
	v_rcp_f32_e32 v83, v77
	ds_read2_b32 v[84:85], v115 offset0:136 offset1:204
	s_cselect_b64 s[48:49], -1, 0
	s_waitcnt lgkmcnt(1)
	v_lshlrev_b32_e32 v81, 16, v78
	v_and_b32_e32 v78, 0xffff0000, v78
	v_mul_f32_e32 v81, v76, v81
	v_mul_f32_e32 v78, v77, v78
	v_pk_mul_f32 v[76:77], v[90:91], v[76:77]
	v_cvt_pk_bf16_f32 v78, v81, v78
	v_rcp_f32_e32 v81, v76
	v_lshlrev_b32_e32 v82, 16, v79
	v_and_b32_e32 v79, 0xffff0000, v79
	v_mul_f32_e32 v82, v76, v82
	v_mul_f32_e32 v79, v77, v79
	v_rcp_f32_e32 v87, v77
	v_cvt_pk_bf16_f32 v79, v82, v79
	ds_write2_b32 v200, v78, v79 offset0:136 offset1:204
	s_waitcnt lgkmcnt(1)
	v_lshlrev_b32_e32 v79, 16, v85
	v_lshlrev_b32_e32 v78, 16, v84
	v_pk_mul_f32 v[88:89], v[178:179], v[80:81] op_sel_hi:[0,1]
	v_pk_mul_f32 v[88:89], v[88:89], v[78:79]
	v_and_b32_e32 v85, 0xffff0000, v85
	v_cvt_pk_bf16_f32 v90, v88, v89
	v_mov_b32_e32 v88, v78
	v_mov_b32_e32 v86, v81
	v_mov_b32_e32 v78, v79
	v_mov_b32_e32 v79, v85
	v_and_b32_e32 v84, 0xffff0000, v84
	v_pk_mul_f32 v[78:79], v[86:87], v[78:79]
	v_mov_b32_e32 v86, v83
	v_mov_b32_e32 v82, v80
	v_mov_b32_e32 v89, v84
	v_pk_mul_f32 v[80:81], v[178:179], v[86:87] op_sel:[1,0]
	v_pk_mul_f32 v[88:89], v[82:83], v[88:89]
	v_pk_mul_f32 v[80:81], v[80:81], v[84:85]
	v_cvt_pk_bf16_f32 v78, v78, v79
	v_cvt_pk_bf16_f32 v80, v80, v81
	v_cvt_pk_bf16_f32 v81, v88, v89
	ds_write2_b32 v115, v81, v78 offset0:136 offset1:204
	ds_write_b32 v193, v90 offset:34820
	ds_write_b32 v193, v80 offset:34964
	v_add_u32_e32 v90, 0x400, v200
	ds_read2_b32 v[78:79], v90 offset0:16 offset1:84
	v_pk_mul_f32 v[76:77], v[92:93], v[76:77]
	v_add_u32_e32 v91, 0x4800, v200
	v_rcp_f32_e32 v80, v76
	v_rcp_f32_e32 v83, v77
	s_waitcnt lgkmcnt(0)
	v_lshlrev_b32_e32 v81, 16, v78
	v_and_b32_e32 v78, 0xffff0000, v78
	ds_read2_b32 v[84:85], v91 offset0:16 offset1:84
	v_mul_f32_e32 v81, v76, v81
	v_mul_f32_e32 v78, v77, v78
	v_pk_mul_f32 v[76:77], v[94:95], v[76:77]
	v_cvt_pk_bf16_f32 v82, v81, v78
	v_rcp_f32_e32 v81, v76
	v_lshlrev_b32_e32 v78, 16, v79
	v_and_b32_e32 v79, 0xffff0000, v79
	v_pk_mul_f32 v[78:79], v[76:77], v[78:79]
	v_rcp_f32_e32 v87, v77
	v_cvt_pk_bf16_f32 v78, v78, v79
	ds_write2_b32 v90, v82, v78 offset0:16 offset1:84
	s_waitcnt lgkmcnt(1)
	v_lshlrev_b32_e32 v79, 16, v85
	v_lshlrev_b32_e32 v78, 16, v84
	v_pk_mul_f32 v[88:89], v[178:179], v[80:81] op_sel_hi:[0,1]
	v_pk_mul_f32 v[88:89], v[88:89], v[78:79]
	v_and_b32_e32 v85, 0xffff0000, v85
	v_cvt_pk_bf16_f32 v92, v88, v89
	v_mov_b32_e32 v88, v78
	v_mov_b32_e32 v86, v81
	v_mov_b32_e32 v78, v79
	v_mov_b32_e32 v79, v85
	v_and_b32_e32 v84, 0xffff0000, v84
	v_pk_mul_f32 v[78:79], v[86:87], v[78:79]
	v_mov_b32_e32 v86, v83
	v_mov_b32_e32 v82, v80
	v_mov_b32_e32 v89, v84
	v_pk_mul_f32 v[80:81], v[178:179], v[86:87] op_sel:[1,0]
	v_pk_mul_f32 v[88:89], v[82:83], v[88:89]
	v_pk_mul_f32 v[80:81], v[80:81], v[84:85]
	v_cvt_pk_bf16_f32 v78, v78, v79
	v_cvt_pk_bf16_f32 v80, v80, v81
	v_cvt_pk_bf16_f32 v81, v88, v89
	ds_write2_b32 v91, v81, v78 offset0:16 offset1:84
	ds_write_b32 v193, v92 offset:34824
	ds_write_b32 v193, v80 offset:34968
	ds_read2_b32 v[78:79], v90 offset0:152 offset1:220
	ds_read2_b32 v[80:81], v91 offset0:152 offset1:220
	v_pk_mul_f32 v[76:77], v[96:97], v[76:77]
	s_and_b64 vcc, exec, s[48:49]
	v_rcp_f32_e32 v85, v77
	s_waitcnt lgkmcnt(1)
	v_lshlrev_b32_e32 v82, 16, v78
	v_and_b32_e32 v83, 0xffff0000, v78
	v_rcp_f32_e32 v78, v76
	v_pk_mul_f32 v[82:83], v[76:77], v[82:83]
	v_pk_mul_f32 v[76:77], v[98:99], v[76:77]
	v_cvt_pk_bf16_f32 v84, v82, v83
	v_lshlrev_b32_e32 v82, 16, v79
	v_and_b32_e32 v83, 0xffff0000, v79
	v_rcp_f32_e32 v79, v76
	v_rcp_f32_e32 v87, v77
	v_pk_mul_f32 v[82:83], v[76:77], v[82:83]
	v_pk_mul_f32 v[76:77], v[162:163], v[76:77]
	v_cvt_pk_bf16_f32 v82, v82, v83
	s_waitcnt lgkmcnt(0)
	v_lshlrev_b32_e32 v83, 16, v81
	v_and_b32_e32 v81, 0xffff0000, v81
	ds_write2_b32 v90, v84, v82 offset0:152 offset1:220
	v_lshlrev_b32_e32 v82, 16, v80
	v_pk_mul_f32 v[88:89], v[178:179], v[78:79] op_sel_hi:[0,1]
	v_mov_b32_e32 v84, v78
	v_mov_b32_e32 v86, v79
	v_mov_b32_e32 v78, v83
	v_mov_b32_e32 v79, v81
	v_pk_mul_f32 v[88:89], v[88:89], v[82:83]
	v_and_b32_e32 v80, 0xffff0000, v80
	v_pk_mul_f32 v[78:79], v[86:87], v[78:79]
	v_mov_b32_e32 v86, v85
	v_cvt_pk_bf16_f32 v90, v88, v89
	v_mov_b32_e32 v88, v82
	v_mov_b32_e32 v89, v80
	v_pk_mul_f32 v[82:83], v[178:179], v[86:87] op_sel:[1,0]
	v_pk_mul_f32 v[88:89], v[84:85], v[88:89]
	v_pk_mul_f32 v[80:81], v[82:83], v[80:81]
	v_cvt_pk_bf16_f32 v78, v78, v79
	v_cvt_pk_bf16_f32 v80, v80, v81
	v_cvt_pk_bf16_f32 v81, v88, v89
	ds_write2_b32 v91, v81, v78 offset0:152 offset1:220
	ds_write_b32 v193, v90 offset:34828
	ds_write_b32 v193, v80 offset:34972
	v_add_u32_e32 v90, 0x800, v200
	ds_read2_b32 v[78:79], v90 offset0:32 offset1:100
	v_add_u32_e32 v91, 0x4c00, v200
	ds_read2_b32 v[80:81], v91 offset0:32 offset1:100
	v_rcp_f32_e32 v85, v77
	s_waitcnt lgkmcnt(1)
	v_lshlrev_b32_e32 v82, 16, v78
	v_and_b32_e32 v83, 0xffff0000, v78
	v_rcp_f32_e32 v78, v76
	v_pk_mul_f32 v[82:83], v[76:77], v[82:83]
	v_pk_mul_f32 v[76:77], v[164:165], v[76:77]
	v_cvt_pk_bf16_f32 v84, v82, v83
	v_lshlrev_b32_e32 v82, 16, v79
	v_and_b32_e32 v83, 0xffff0000, v79
	v_rcp_f32_e32 v79, v76
	v_rcp_f32_e32 v87, v77
	v_pk_mul_f32 v[82:83], v[76:77], v[82:83]
	v_pk_mul_f32 v[76:77], v[166:167], v[76:77]
	v_cvt_pk_bf16_f32 v82, v82, v83
	s_waitcnt lgkmcnt(0)
	v_lshlrev_b32_e32 v83, 16, v81
	v_and_b32_e32 v81, 0xffff0000, v81
	ds_write2_b32 v90, v84, v82 offset0:32 offset1:100
	v_lshlrev_b32_e32 v82, 16, v80
	v_pk_mul_f32 v[88:89], v[178:179], v[78:79] op_sel_hi:[0,1]
	v_mov_b32_e32 v84, v78
	v_mov_b32_e32 v86, v79
	v_mov_b32_e32 v78, v83
	v_mov_b32_e32 v79, v81
	v_pk_mul_f32 v[88:89], v[88:89], v[82:83]
	v_and_b32_e32 v80, 0xffff0000, v80
	v_pk_mul_f32 v[78:79], v[86:87], v[78:79]
	v_mov_b32_e32 v86, v85
	v_cvt_pk_bf16_f32 v92, v88, v89
	v_mov_b32_e32 v88, v82
	v_mov_b32_e32 v89, v80
	v_pk_mul_f32 v[82:83], v[178:179], v[86:87] op_sel:[1,0]
	v_pk_mul_f32 v[88:89], v[84:85], v[88:89]
	v_pk_mul_f32 v[80:81], v[82:83], v[80:81]
	v_cvt_pk_bf16_f32 v78, v78, v79
	v_cvt_pk_bf16_f32 v80, v80, v81
	v_cvt_pk_bf16_f32 v81, v88, v89
	ds_write2_b32 v91, v81, v78 offset0:32 offset1:100
	ds_write_b32 v193, v92 offset:34832
	ds_write_b32 v193, v80 offset:34976
	ds_read2_b32 v[78:79], v90 offset0:168 offset1:236
	ds_read2_b32 v[80:81], v91 offset0:168 offset1:236
	v_rcp_f32_e32 v85, v77
	s_waitcnt lgkmcnt(1)
	v_lshlrev_b32_e32 v82, 16, v78
	v_and_b32_e32 v83, 0xffff0000, v78
	v_rcp_f32_e32 v78, v76
	v_pk_mul_f32 v[82:83], v[76:77], v[82:83]
	v_pk_mul_f32 v[76:77], v[168:169], v[76:77]
	v_cvt_pk_bf16_f32 v84, v82, v83
	v_lshlrev_b32_e32 v82, 16, v79
	v_and_b32_e32 v83, 0xffff0000, v79
	v_rcp_f32_e32 v79, v76
	v_rcp_f32_e32 v87, v77
	v_pk_mul_f32 v[82:83], v[76:77], v[82:83]
	v_pk_mul_f32 v[76:77], v[170:171], v[76:77]
	v_cvt_pk_bf16_f32 v82, v82, v83
	s_waitcnt lgkmcnt(0)
	v_lshlrev_b32_e32 v83, 16, v81
	v_and_b32_e32 v81, 0xffff0000, v81
	ds_write2_b32 v90, v84, v82 offset0:168 offset1:236
	v_lshlrev_b32_e32 v82, 16, v80
	v_pk_mul_f32 v[88:89], v[178:179], v[78:79] op_sel_hi:[0,1]
	v_mov_b32_e32 v84, v78
	v_mov_b32_e32 v86, v79
	v_mov_b32_e32 v78, v83
	v_mov_b32_e32 v79, v81
	v_pk_mul_f32 v[88:89], v[88:89], v[82:83]
	v_and_b32_e32 v80, 0xffff0000, v80
	v_pk_mul_f32 v[78:79], v[86:87], v[78:79]
	v_mov_b32_e32 v86, v85
	v_cvt_pk_bf16_f32 v90, v88, v89
	v_mov_b32_e32 v88, v82
	v_mov_b32_e32 v89, v80
	v_pk_mul_f32 v[82:83], v[178:179], v[86:87] op_sel:[1,0]
	v_pk_mul_f32 v[88:89], v[84:85], v[88:89]
	v_pk_mul_f32 v[80:81], v[82:83], v[80:81]
	v_cvt_pk_bf16_f32 v78, v78, v79
	v_cvt_pk_bf16_f32 v80, v80, v81
	v_cvt_pk_bf16_f32 v81, v88, v89
	ds_write2_b32 v91, v81, v78 offset0:168 offset1:236
	ds_write_b32 v193, v90 offset:34836
	ds_write_b32 v193, v80 offset:34980
	v_add_u32_e32 v90, 0xc00, v200
	ds_read2_b32 v[78:79], v90 offset0:48 offset1:116
	v_add_u32_e32 v91, 0x5000, v200
	ds_read2_b32 v[80:81], v91 offset0:48 offset1:116
	v_rcp_f32_e32 v85, v77
	s_waitcnt lgkmcnt(1)
	v_lshlrev_b32_e32 v82, 16, v78
	v_and_b32_e32 v83, 0xffff0000, v78
	v_rcp_f32_e32 v78, v76
	v_pk_mul_f32 v[82:83], v[76:77], v[82:83]
	v_pk_mul_f32 v[76:77], v[172:173], v[76:77]
	v_cvt_pk_bf16_f32 v84, v82, v83
	v_lshlrev_b32_e32 v82, 16, v79
	v_and_b32_e32 v83, 0xffff0000, v79
	v_rcp_f32_e32 v79, v76
	v_rcp_f32_e32 v87, v77
	v_pk_mul_f32 v[82:83], v[76:77], v[82:83]
	v_pk_mul_f32 v[76:77], v[174:175], v[76:77]
	v_cvt_pk_bf16_f32 v82, v82, v83
	s_waitcnt lgkmcnt(0)
	v_lshlrev_b32_e32 v83, 16, v81
	v_and_b32_e32 v81, 0xffff0000, v81
	ds_write2_b32 v90, v84, v82 offset0:48 offset1:116
	v_lshlrev_b32_e32 v82, 16, v80
	v_pk_mul_f32 v[88:89], v[178:179], v[78:79] op_sel_hi:[0,1]
	v_mov_b32_e32 v84, v78
	v_mov_b32_e32 v86, v79
	v_mov_b32_e32 v78, v83
	v_mov_b32_e32 v79, v81
	v_pk_mul_f32 v[88:89], v[88:89], v[82:83]
	v_and_b32_e32 v80, 0xffff0000, v80
	v_pk_mul_f32 v[78:79], v[86:87], v[78:79]
	v_mov_b32_e32 v86, v85
	v_cvt_pk_bf16_f32 v92, v88, v89
	v_mov_b32_e32 v88, v82
	v_mov_b32_e32 v89, v80
	v_pk_mul_f32 v[82:83], v[178:179], v[86:87] op_sel:[1,0]
	v_pk_mul_f32 v[88:89], v[84:85], v[88:89]
	v_pk_mul_f32 v[80:81], v[82:83], v[80:81]
	v_cvt_pk_bf16_f32 v78, v78, v79
	v_cvt_pk_bf16_f32 v80, v80, v81
	v_cvt_pk_bf16_f32 v81, v88, v89
	ds_write2_b32 v91, v81, v78 offset0:48 offset1:116
	ds_write_b32 v193, v92 offset:34840
	ds_write_b32 v193, v80 offset:34984
	ds_read2_b32 v[78:79], v90 offset0:184 offset1:252
	ds_read2_b32 v[80:81], v91 offset0:184 offset1:252
	v_rcp_f32_e32 v85, v77
	s_waitcnt lgkmcnt(1)
	v_lshlrev_b32_e32 v82, 16, v78
	v_and_b32_e32 v83, 0xffff0000, v78
	v_rcp_f32_e32 v78, v76
	v_pk_mul_f32 v[82:83], v[76:77], v[82:83]
	v_pk_mul_f32 v[76:77], v[176:177], v[76:77]
	v_cvt_pk_bf16_f32 v84, v82, v83
	v_lshlrev_b32_e32 v82, 16, v79
	v_and_b32_e32 v83, 0xffff0000, v79
	v_rcp_f32_e32 v79, v76
	v_rcp_f32_e32 v87, v77
	v_pk_mul_f32 v[76:77], v[76:77], v[82:83]
	v_pk_mul_f32 v[82:83], v[178:179], v[78:79] op_sel_hi:[0,1]
	v_cvt_pk_bf16_f32 v76, v76, v77
	ds_write2_b32 v90, v84, v76 offset0:184 offset1:252
	s_waitcnt lgkmcnt(1)
	v_lshlrev_b32_e32 v77, 16, v81
	v_lshlrev_b32_e32 v76, 16, v80
	v_pk_mul_f32 v[82:83], v[82:83], v[76:77]
	v_and_b32_e32 v81, 0xffff0000, v81
	v_cvt_pk_bf16_f32 v88, v82, v83
	v_mov_b32_e32 v82, v76
	v_mov_b32_e32 v86, v79
	v_mov_b32_e32 v76, v77
	v_mov_b32_e32 v77, v81
	v_and_b32_e32 v80, 0xffff0000, v80
	v_pk_mul_f32 v[76:77], v[86:87], v[76:77]
	v_mov_b32_e32 v86, v85
	v_mov_b32_e32 v84, v78
	v_mov_b32_e32 v83, v80
	v_pk_mul_f32 v[78:79], v[178:179], v[86:87] op_sel:[1,0]
	v_pk_mul_f32 v[82:83], v[84:85], v[82:83]
	v_pk_mul_f32 v[78:79], v[78:79], v[80:81]
	v_cvt_pk_bf16_f32 v76, v76, v77
	v_cvt_pk_bf16_f32 v78, v78, v79
	v_cvt_pk_bf16_f32 v79, v82, v83
	ds_write2_b32 v91, v79, v76 offset0:184 offset1:252
	ds_write_b32 v193, v88 offset:34844
	ds_write_b32 v193, v78 offset:34988
	s_waitcnt lgkmcnt(0)
	s_barrier
	s_cbranch_vccnz .LBB0_3095
	ds_read_b128 v[76:79], v198
	v_add_u32_e32 v115, v196, v201
	ds_read_b128 v[80:83], v115 offset:17408
	ds_read_b128 v[84:87], v198 offset:64
	ds_read_b128 v[88:91], v115 offset:17472
	ds_read_b128 v[92:95], v115 offset:21760
	ds_read_b128 v[96:99], v115 offset:21824
	ds_read_b128 v[162:165], v115 offset:26112
	ds_read_b128 v[166:169], v115 offset:26176
	ds_read_b128 v[170:173], v115 offset:30464
	ds_read_b128 v[174:177], v115 offset:30528
	s_waitcnt lgkmcnt(8)
	v_mfma_f32_16x16x32_bf16 v[80:83], v[76:79], v[80:83], 0
	s_waitcnt lgkmcnt(5)
	v_mfma_f32_16x16x32_bf16 v[92:95], v[76:79], v[92:95], 0
	s_waitcnt lgkmcnt(3)
	v_mfma_f32_16x16x32_bf16 v[162:165], v[76:79], v[162:165], 0
	s_waitcnt lgkmcnt(1)
	v_mfma_f32_16x16x32_bf16 v[76:79], v[76:79], v[170:173], 0
	ds_read_b128 v[170:173], v198 offset:128
	ds_read_b128 v[216:219], v115 offset:17536
	v_mfma_f32_16x16x32_bf16 v[80:83], v[84:87], v[88:91], v[80:83]
	ds_read_b128 v[88:91], v198 offset:192
	ds_read_b128 v[220:223], v115 offset:17600
	s_waitcnt lgkmcnt(2)
	v_mfma_f32_16x16x32_bf16 v[80:83], v[170:173], v[216:219], v[80:83]
	ds_read_b128 v[216:219], v115 offset:21888
	ds_read_b128 v[224:227], v115 offset:21952
	ds_read_b128 v[228:231], v115 offset:26240
	ds_read_b128 v[232:235], v115 offset:26304
	s_waitcnt lgkmcnt(4)
	v_mfma_f32_16x16x32_bf16 v[80:83], v[88:91], v[220:223], v[80:83]
	ds_read_b128 v[220:223], v115 offset:30592
	ds_read_b128 v[236:239], v115 offset:30656
	v_mfma_f32_16x16x32_bf16 v[92:95], v[84:87], v[96:99], v[92:95]
	s_nop 4
	v_cvt_pk_bf16_f32 v80, v80, s0
	v_cndmask_b32_e64 v80, v80, 0, s[12:13]
	ds_write_b16 v204, v80 offset:62464
	v_cvt_pk_bf16_f32 v80, v81, s0
	v_cndmask_b32_e64 v80, v80, 0, s[14:15]
	s_waitcnt lgkmcnt(6)
	v_mfma_f32_16x16x32_bf16 v[92:95], v[170:173], v[216:219], v[92:95]
	ds_write_b16 v204, v80 offset:62608
	v_cvt_pk_bf16_f32 v80, v82, s0
	v_cndmask_b32_e64 v80, v80, 0, s[16:17]
	ds_write_b16 v204, v80 offset:62752
	v_cvt_pk_bf16_f32 v80, v83, s0
	v_cndmask_b32_e64 v115, v80, 0, s[18:19]
	s_waitcnt lgkmcnt(7)
	v_mfma_f32_16x16x32_bf16 v[80:83], v[88:91], v[224:227], v[92:95]
	ds_write_b16 v204, v115 offset:62896
	v_mfma_f32_16x16x32_bf16 v[96:99], v[84:87], v[166:169], v[162:165]
	v_mfma_f32_16x16x32_bf16 v[76:79], v[84:87], v[174:177], v[76:79]
	s_nop 4
	v_cvt_pk_bf16_f32 v80, v80, s0
	v_cndmask_b32_e64 v80, v80, 0, s[20:21]
	ds_write_b16 v204, v80 offset:62496
	v_cvt_pk_bf16_f32 v80, v81, s0
	v_cndmask_b32_e64 v80, v80, 0, s[22:23]
	s_waitcnt lgkmcnt(8)
	v_mfma_f32_16x16x32_bf16 v[84:87], v[170:173], v[228:231], v[96:99]
	ds_write_b16 v204, v80 offset:62640
	v_cvt_pk_bf16_f32 v80, v82, s0
	v_cndmask_b32_e64 v80, v80, 0, s[24:25]
	s_waitcnt lgkmcnt(7)
	v_mfma_f32_16x16x32_bf16 v[76:79], v[170:173], v[220:223], v[76:79]
	ds_write_b16 v204, v80 offset:62784
	v_cvt_pk_bf16_f32 v80, v83, s0
	v_cndmask_b32_e64 v92, v80, 0, s[26:27]
	v_mfma_f32_16x16x32_bf16 v[80:83], v[88:91], v[232:235], v[84:87]
	ds_write_b16 v204, v92 offset:62928
	s_waitcnt lgkmcnt(8)
	v_mfma_f32_16x16x32_bf16 v[76:79], v[88:91], v[236:239], v[76:79]
	s_nop 4
	v_cvt_pk_bf16_f32 v80, v80, s0
	s_nop 1
	v_cvt_pk_bf16_f32 v76, v76, s0
	v_cndmask_b32_e64 v80, v80, 0, s[28:29]
	v_cndmask_b32_e64 v76, v76, 0, s[38:39]
	ds_write_b16 v204, v80 offset:62528
	v_cvt_pk_bf16_f32 v80, v81, s0
	ds_write_b16 v204, v76 offset:62560
	v_cvt_pk_bf16_f32 v76, v77, s0
	v_cndmask_b32_e64 v80, v80, 0, s[30:31]
	v_cndmask_b32_e64 v76, v76, 0, s[40:41]
	ds_write_b16 v204, v80 offset:62672
	v_cvt_pk_bf16_f32 v80, v82, s0
	ds_write_b16 v204, v76 offset:62704
	v_cvt_pk_bf16_f32 v76, v78, s0
	v_cndmask_b32_e64 v80, v80, 0, s[34:35]
	v_cndmask_b32_e64 v76, v76, 0, s[42:43]
	ds_write_b16 v204, v80 offset:62816
	v_cvt_pk_bf16_f32 v80, v83, s0
	ds_write_b16 v204, v76 offset:62848
	v_cvt_pk_bf16_f32 v76, v79, s0
	v_cndmask_b32_e64 v80, v80, 0, s[36:37]
	v_cndmask_b32_e64 v76, v76, 0, s[44:45]
	ds_write_b16 v204, v80 offset:62960
	ds_write_b16 v204, v76 offset:62992
